# loop-edge edits in the differential attention steady loop: slot rotation / tile counter ahead of each closing barrier, rescale blocks out of line (fall-through common path)
# baseline (speedup 1.0000x reference)
; #define WAIT_BAR(N) asm volatile("s_waitcnt vmcnt(" #N ") lgkmcnt(0)\n\ts_barrier":::"memory")
;   #define RESC() do{ if(resc){ asm volatile("s_waitcnt lgkmcnt(0)":::"memory"); \
;       _Pragma("unroll") for(int d_=0;d_<2;++d_) _Pragma("unroll") for(int r=0;r<16;++r)o[d_][r]*=wsf[crow(r,hi)]; } }while(0)
;   #define ROT() do{sl_prev=sl_cur;sl_cur=sl_next;sl_next=(sl_next==(NSLOT-1)*SLOTB)?0:sl_next+SLOTB;}while(0)
;   #define RESC() do{ if(resc){ asm volatile("s_waitcnt lgkmcnt(0)":::"memory"); \
;       _Pragma("unroll") for(int d_=0;d_<4;++d_) _Pragma("unroll") for(int r=0;r<16;++r)o[d_][r]*=wsf[crow(r,hi)]; } }while(0)
;   #define ROT() do{sl_prev=sl_cur;sl_cur=sl_next;sl_next=(sl_next==(NSLOT-1)*SLOTB)?0:sl_next+SLOTB;}while(0)
; template<int THRL> __device__ __forceinline__ void attn_unit_d(int qb,const bf16*Q,const bf16*__restrict__ K,const bf16*__restrict__ V,bf16*O,const float*__restrict__ cum,const float*__restrict__ relb,const float thr,char*shm,const int wv){
;     ...
;   int t=1;
;     ...
;   constexpr int NEAR=(MODE==1)?7:5;
;   for(;t+NEAR<NT;t+=2){
;     STEP(pB0,pB1,pA0,pA1,t,true,true,true);     WAIT_BAR(3); RESC(); ROT();
.LBB0_470:
	s_waitcnt lgkmcnt(14)
	v_mfma_f32_32x32x16_bf16 v[64:79], v[156:159], v[208:211], v[64:79]
	v_exp_f32_e32 v96, v80
	v_exp_f32_e32 v97, v81
	ds_read_b64_tr_b16 v[116:117], v212 offset:32768
	ds_read_b64_tr_b16 v[118:119], v212 offset:33280
	s_waitcnt lgkmcnt(14)
	v_mfma_f32_32x32x16_bf16 v[48:63], v[156:159], v[204:207], v[48:63]
	v_exp_f32_e32 v98, v98
	v_exp_f32_e32 v99, v99
	ds_read_b64_tr_b16 v[120:121], v212 offset:36864
	ds_read_b64_tr_b16 v[122:123], v212 offset:37376
	v_add_u32_e32 v80, s40, v249
	ds_read_b128 v[112:115], v80
	ds_read_b128 v[128:131], v80 offset:512
	s_waitcnt lgkmcnt(14)
	v_mfma_f32_32x32x16_bf16 v[64:79], v[152:155], v[10:13], v[64:79]
	v_exp_f32_e32 v100, v100
	v_exp_f32_e32 v101, v101
	ds_read_b64_tr_b16 v[124:125], v212 offset:33792
	ds_read_b64_tr_b16 v[126:127], v212 offset:34304
	ds_read_b128 v[184:187], v80 offset:2048
	ds_read_b128 v[176:179], v80 offset:2560
	v_mfma_f32_32x32x16_bf16 v[48:63], v[152:155], v[6:9], v[48:63]
	v_exp_f32_e32 v102, v102
	v_exp_f32_e32 v103, v103
	ds_read_b64_tr_b16 v[132:133], v212 offset:37888
	ds_read_b64_tr_b16 v[134:135], v212 offset:38400
	ds_read_b128 v[180:183], v80 offset:4096
	ds_read_b128 v[6:9], v80 offset:4608
	s_waitcnt lgkmcnt(14)
	v_mfma_f32_32x32x16_bf16 v[64:79], v[148:151], v[2:5], v[64:79]
	v_exp_f32_e32 v104, v104
	v_exp_f32_e32 v105, v105
	ds_read_b64_tr_b16 v[136:137], v212 offset:34816
	ds_read_b64_tr_b16 v[138:139], v212 offset:35328
	ds_read_b128 v[10:13], v80 offset:6144
	ds_read_b128 v[2:5], v80 offset:6656
	v_mfma_f32_32x32x16_bf16 v[48:63], v[148:151], v[188:191], v[48:63]
	v_exp_f32_e32 v106, v106
	v_exp_f32_e32 v107, v107
	ds_read_b64_tr_b16 v[140:141], v212 offset:38912
	ds_read_b64_tr_b16 v[142:143], v212 offset:39424
	v_mfma_f32_32x32x16_bf16 v[64:79], v[144:147], v[192:195], v[64:79]
	v_exp_f32_e32 v108, v108
	v_exp_f32_e32 v109, v109
	ds_read_b64_tr_b16 v[188:189], v212 offset:35840
	ds_read_b64_tr_b16 v[190:191], v212 offset:36352
	v_mfma_f32_32x32x16_bf16 v[48:63], v[144:147], v[196:199], v[48:63]
	v_exp_f32_e32 v110, v110
	v_exp_f32_e32 v111, v111
	ds_read_b64_tr_b16 v[192:193], v212 offset:39936
	ds_read_b64_tr_b16 v[194:195], v212 offset:40448
	s_waitcnt lgkmcnt(14)
	v_mfma_f32_32x32x16_bf16 v[32:47], v[156:159], v[116:119], v[32:47]
	v_exp_f32_e32 v80, v14
	v_exp_f32_e32 v81, v15
	v_mfma_f32_32x32x16_bf16 v[16:31], v[156:159], v[120:123], v[16:31]
	v_exp_f32_e32 v82, v82
	v_exp_f32_e32 v83, v83
	v_mfma_f32_32x32x16_bf16 v[32:47], v[152:155], v[124:127], v[32:47]
	v_exp_f32_e32 v84, v84
	v_exp_f32_e32 v85, v85
	s_waitcnt lgkmcnt(12)
	v_mfma_f32_32x32x16_bf16 v[16:31], v[152:155], v[132:135], v[16:31]
	v_exp_f32_e32 v86, v86
	v_exp_f32_e32 v87, v87
	s_waitcnt lgkmcnt(8)
	v_mfma_f32_32x32x16_bf16 v[32:47], v[148:151], v[136:139], v[32:47]
	v_exp_f32_e32 v88, v88
	v_exp_f32_e32 v89, v89
	s_waitcnt lgkmcnt(4)
	v_mfma_f32_32x32x16_bf16 v[16:31], v[148:151], v[140:143], v[16:31]
	v_exp_f32_e32 v90, v90
	v_exp_f32_e32 v91, v91
	s_waitcnt lgkmcnt(2)
	v_mfma_f32_32x32x16_bf16 v[32:47], v[144:147], v[188:191], v[32:47]
	v_exp_f32_e32 v92, v92
	v_exp_f32_e32 v93, v93
	s_waitcnt lgkmcnt(0)
	v_mfma_f32_32x32x16_bf16 v[16:31], v[144:147], v[192:195], v[16:31]
	v_exp_f32_e32 v94, v94
	v_exp_f32_e32 v95, v95
	s_add_i32 s44, s40, 0x2000
	s_cmpk_lg_i32 s40, 0x4000
	s_cselect_b32 s91, s44, 0
	s_waitcnt vmcnt(3) lgkmcnt(0)
	s_barrier
	s_andn2_b64 vcc, exec, s[6:7]
	s_cbranch_vccz .Lresc1_l0
.LBB0_472:
	s_lshl_b32 s6, s48, 1
	v_add_u32_e32 v14, s6, v250
	ds_read_b64_tr_b16 v[192:193], v14 offset:24576
	ds_read_b64_tr_b16 v[194:195], v14 offset:25088
	v_add_f32_e32 v15, v96, v97
	v_add_f32_e32 v15, v98, v15
	v_add_f32_e32 v15, v99, v15
	v_add_f32_e32 v15, v100, v15
	v_add_f32_e32 v15, v101, v15
	v_cvt_pk_bf16_f32 v156, v96, v97
	v_cvt_pk_bf16_f32 v157, v98, v99
	v_mfma_f32_32x32x16_bf16 v[112:127], v[112:115], v[172:175], 0
	ds_read_b64_tr_b16 v[196:197], v14 offset:28672
	ds_read_b64_tr_b16 v[198:199], v14 offset:29184
	v_add_f32_e32 v15, v102, v15
	v_add_f32_e32 v15, v103, v15
	v_add_f32_e32 v15, v104, v15
	v_add_f32_e32 v15, v105, v15
	v_cvt_pk_bf16_f32 v158, v100, v101
	v_cvt_pk_bf16_f32 v159, v102, v103
	v_mfma_f32_32x32x16_bf16 v[128:143], v[128:131], v[172:175], 0
	ds_read_b64_tr_b16 v[188:189], v14 offset:25600
	ds_read_b64_tr_b16 v[190:191], v14 offset:26112
	v_add_f32_e32 v15, v106, v15
	v_add_f32_e32 v15, v107, v15
	v_add_f32_e32 v15, v108, v15
	v_add_f32_e32 v15, v109, v15
	v_cvt_pk_bf16_f32 v152, v104, v105
	v_cvt_pk_bf16_f32 v153, v106, v107
	v_mfma_f32_32x32x16_bf16 v[112:127], v[184:187], v[168:171], v[112:127]
	ds_read_b64_tr_b16 v[184:185], v14 offset:29696
	ds_read_b64_tr_b16 v[186:187], v14 offset:30208
	v_add_f32_e32 v15, v110, v15
	v_add_f32_e32 v15, v111, v15
	v_add_f32_e32 v15, v80, v15
	v_add_f32_e32 v15, v81, v15
	v_cvt_pk_bf16_f32 v154, v108, v109
	v_cvt_pk_bf16_f32 v155, v110, v111
	v_mfma_f32_32x32x16_bf16 v[128:143], v[176:179], v[168:171], v[128:143]
	ds_read_b64_tr_b16 v[176:177], v14 offset:26624
	ds_read_b64_tr_b16 v[178:179], v14 offset:27136
	v_add_f32_e32 v15, v82, v15
	v_add_f32_e32 v15, v83, v15
	v_add_f32_e32 v15, v84, v15
	v_add_f32_e32 v15, v85, v15
	v_cvt_pk_bf16_f32 v148, v80, v81
	v_cvt_pk_bf16_f32 v149, v82, v83
	v_mfma_f32_32x32x16_bf16 v[112:127], v[180:183], v[164:167], v[112:127]
	ds_read_b64_tr_b16 v[208:209], v14 offset:30720
	ds_read_b64_tr_b16 v[210:211], v14 offset:31232
	v_add_f32_e32 v15, v86, v15
	v_add_f32_e32 v15, v87, v15
	v_add_f32_e32 v15, v88, v15
	v_add_f32_e32 v15, v89, v15
	v_cvt_pk_bf16_f32 v150, v84, v85
	v_cvt_pk_bf16_f32 v151, v86, v87
	v_mfma_f32_32x32x16_bf16 v[128:143], v[6:9], v[164:167], v[128:143]
	ds_read_b64_tr_b16 v[6:7], v14 offset:27648
	ds_read_b64_tr_b16 v[8:9], v14 offset:28160
	v_add_f32_e32 v15, v90, v15
	v_add_f32_e32 v15, v91, v15
	v_add_f32_e32 v15, v92, v15
	v_add_f32_e32 v15, v93, v15
	v_cvt_pk_bf16_f32 v144, v88, v89
	v_cvt_pk_bf16_f32 v145, v90, v91
	v_mfma_f32_32x32x16_bf16 v[112:127], v[10:13], v[160:163], v[112:127]
	ds_read_b64_tr_b16 v[10:11], v14 offset:31744
	ds_read_b64_tr_b16 v[12:13], v14 offset:32256
	v_add_f32_e32 v15, v94, v15
	v_add_f32_e32 v15, v95, v15
	v_add_f32_e32 v15, 0, v15
	v_cvt_pk_bf16_f32 v146, v92, v93
	v_cvt_pk_bf16_f32 v147, v94, v95
	v_mfma_f32_32x32x16_bf16 v[128:143], v[2:5], v[160:163], v[128:143]
	s_add_i32 s6, s40, s77
	s_mov_b32 m0, s6
	s_add_i32 s41, s41, 0x8000
	buffer_load_dwordx4 v247, s[12:15], s41 offen lds
	s_lshl_b32 s6, s91, 1
	s_add_i32 s48, s43, 0x8000
	s_add_i32 s7, s6, s81
	s_mov_b32 m0, s7
	s_nop 0
	buffer_load_dwordx4 v248, s[16:19], s48 offen lds
	s_add_i32 s7, s43, 0x8080
	s_add_i32 s6, s6, s55
	s_mov_b32 m0, s6
	s_nop 0
	buffer_load_dwordx4 v248, s[16:19], s7 offen lds
	v_add_f32_e64 v4, v112, -v228
	v_add_f32_e64 v5, v113, -v228
	v_pk_add_f32 v[2:3], v[128:129], v[228:229] op_sel_hi:[1,0] neg_lo:[0,1] neg_hi:[0,1]
	v_pk_add_f32 v[98:99], v[114:115], v[228:229] op_sel_hi:[1,0] neg_lo:[0,1] neg_hi:[0,1]
	v_pk_add_f32 v[82:83], v[130:131], v[228:229] op_sel_hi:[1,0] neg_lo:[0,1] neg_hi:[0,1]
	v_max_f32_e32 v80, v4, v5
	v_pk_add_f32 v[100:101], v[116:117], v[228:229] op_sel_hi:[1,0] neg_lo:[0,1] neg_hi:[0,1]
	v_pk_add_f32 v[102:103], v[118:119], v[228:229] op_sel_hi:[1,0] neg_lo:[0,1] neg_hi:[0,1]
	v_max3_f32 v81, v98, v99, v3
	v_max3_f32 v80, v80, v2, v82
	v_pk_add_f32 v[84:85], v[132:133], v[228:229] op_sel_hi:[1,0] neg_lo:[0,1] neg_hi:[0,1]
	v_pk_add_f32 v[86:87], v[134:135], v[228:229] op_sel_hi:[1,0] neg_lo:[0,1] neg_hi:[0,1]
	v_max3_f32 v80, v80, v83, v100
	v_max3_f32 v81, v81, v102, v103
	v_pk_add_f32 v[104:105], v[120:121], v[228:229] op_sel_hi:[1,0] neg_lo:[0,1] neg_hi:[0,1]
	v_pk_add_f32 v[106:107], v[122:123], v[228:229] op_sel_hi:[1,0] neg_lo:[0,1] neg_hi:[0,1]
	v_max3_f32 v80, v80, v101, v84
	v_max3_f32 v81, v81, v86, v87
	v_pk_add_f32 v[88:89], v[136:137], v[228:229] op_sel_hi:[1,0] neg_lo:[0,1] neg_hi:[0,1]
	v_pk_add_f32 v[90:91], v[138:139], v[228:229] op_sel_hi:[1,0] neg_lo:[0,1] neg_hi:[0,1]
	v_max3_f32 v80, v80, v85, v104
	v_max3_f32 v81, v81, v106, v107
	v_pk_add_f32 v[108:109], v[124:125], v[228:229] op_sel_hi:[1,0] neg_lo:[0,1] neg_hi:[0,1]
	v_pk_add_f32 v[110:111], v[126:127], v[228:229] op_sel_hi:[1,0] neg_lo:[0,1] neg_hi:[0,1]
	v_max3_f32 v80, v80, v105, v88
	v_max3_f32 v81, v81, v90, v91
	v_pk_add_f32 v[92:93], v[140:141], v[228:229] op_sel_hi:[1,0] neg_lo:[0,1] neg_hi:[0,1]
	v_pk_add_f32 v[94:95], v[142:143], v[228:229] op_sel_hi:[1,0] neg_lo:[0,1] neg_hi:[0,1]
	v_max3_f32 v80, v80, v89, v108
	v_max3_f32 v81, v81, v110, v111
	v_max3_f32 v80, v80, v109, v92
	v_max3_f32 v81, v81, v94, v95
	v_add_f32_e32 v251, v0, v15
	v_max3_f32 v0, v80, v93, v81
	v_cmp_lt_f32_e32 vcc, s83, v0
	s_cmp_lg_u64 vcc, 0
	s_cselect_b64 s[6:7], -1, 0
	s_cbranch_vccnz .LBB0_480
.LBB0_473:
	s_waitcnt lgkmcnt(14)
	v_mfma_f32_32x32x16_bf16 v[64:79], v[156:159], v[192:195], v[64:79]
	v_exp_f32_e32 v96, v4
	v_exp_f32_e32 v97, v5
	ds_read_b64_tr_b16 v[112:113], v14 offset:32768
	ds_read_b64_tr_b16 v[114:115], v14 offset:33280
	s_waitcnt lgkmcnt(14)
	v_mfma_f32_32x32x16_bf16 v[48:63], v[156:159], v[196:199], v[48:63]
	v_exp_f32_e32 v98, v98
	v_exp_f32_e32 v99, v99
	ds_read_b64_tr_b16 v[116:117], v14 offset:36864
	ds_read_b64_tr_b16 v[118:119], v14 offset:37376
	v_add_u32_e32 v0, s91, v249
	ds_read_b128 v[204:207], v0
	ds_read_b128 v[200:203], v0 offset:512
	s_waitcnt lgkmcnt(14)
	v_mfma_f32_32x32x16_bf16 v[64:79], v[152:155], v[188:191], v[64:79]
	v_exp_f32_e32 v100, v100
	v_exp_f32_e32 v101, v101
	ds_read_b64_tr_b16 v[120:121], v14 offset:33792
	ds_read_b64_tr_b16 v[122:123], v14 offset:34304
	ds_read_b128 v[196:199], v0 offset:2048
	ds_read_b128 v[192:195], v0 offset:2560
	v_mfma_f32_32x32x16_bf16 v[48:63], v[152:155], v[184:187], v[48:63]
	v_exp_f32_e32 v102, v102
	v_exp_f32_e32 v103, v103
	ds_read_b64_tr_b16 v[124:125], v14 offset:37888
	ds_read_b64_tr_b16 v[126:127], v14 offset:38400
	ds_read_b128 v[188:191], v0 offset:4096
	ds_read_b128 v[184:187], v0 offset:4608
	s_waitcnt lgkmcnt(14)
	v_mfma_f32_32x32x16_bf16 v[64:79], v[148:151], v[176:179], v[64:79]
	v_exp_f32_e32 v104, v104
	v_exp_f32_e32 v105, v105
	ds_read_b64_tr_b16 v[128:129], v14 offset:34816
	ds_read_b64_tr_b16 v[130:131], v14 offset:35328
	ds_read_b128 v[180:183], v0 offset:6144
	ds_read_b128 v[176:179], v0 offset:6656
	v_mfma_f32_32x32x16_bf16 v[48:63], v[148:151], v[208:211], v[48:63]
	v_exp_f32_e32 v106, v106
	v_exp_f32_e32 v107, v107
	ds_read_b64_tr_b16 v[132:133], v14 offset:38912
	ds_read_b64_tr_b16 v[134:135], v14 offset:39424
	v_mfma_f32_32x32x16_bf16 v[64:79], v[144:147], v[6:9], v[64:79]
	v_exp_f32_e32 v108, v108
	v_exp_f32_e32 v109, v109
	ds_read_b64_tr_b16 v[4:5], v14 offset:35840
	ds_read_b64_tr_b16 v[6:7], v14 offset:36352
	v_mfma_f32_32x32x16_bf16 v[48:63], v[144:147], v[10:13], v[48:63]
	v_exp_f32_e32 v110, v110
	v_exp_f32_e32 v111, v111
	ds_read_b64_tr_b16 v[8:9], v14 offset:39936
	ds_read_b64_tr_b16 v[10:11], v14 offset:40448
	s_waitcnt lgkmcnt(14)
	v_mfma_f32_32x32x16_bf16 v[32:47], v[156:159], v[112:115], v[32:47]
	v_exp_f32_e32 v80, v2
	v_exp_f32_e32 v81, v3
	v_mfma_f32_32x32x16_bf16 v[16:31], v[156:159], v[116:119], v[16:31]
	v_exp_f32_e32 v82, v82
	v_exp_f32_e32 v83, v83
	v_mfma_f32_32x32x16_bf16 v[32:47], v[152:155], v[120:123], v[32:47]
	v_exp_f32_e32 v84, v84
	v_exp_f32_e32 v85, v85
	s_waitcnt lgkmcnt(12)
	v_mfma_f32_32x32x16_bf16 v[16:31], v[152:155], v[124:127], v[16:31]
	v_exp_f32_e32 v86, v86
	v_exp_f32_e32 v87, v87
	s_waitcnt lgkmcnt(8)
	v_mfma_f32_32x32x16_bf16 v[32:47], v[148:151], v[128:131], v[32:47]
	v_exp_f32_e32 v88, v88
	v_exp_f32_e32 v89, v89
	s_waitcnt lgkmcnt(4)
	v_mfma_f32_32x32x16_bf16 v[16:31], v[148:151], v[132:135], v[16:31]
	v_exp_f32_e32 v90, v90
	v_exp_f32_e32 v91, v91
	s_waitcnt lgkmcnt(2)
	v_mfma_f32_32x32x16_bf16 v[32:47], v[144:147], v[4:7], v[32:47]
	v_exp_f32_e32 v92, v92
	v_exp_f32_e32 v93, v93
	s_waitcnt lgkmcnt(0)
	v_mfma_f32_32x32x16_bf16 v[16:31], v[144:147], v[8:11], v[16:31]
	v_exp_f32_e32 v94, v94
	v_exp_f32_e32 v95, v95
	s_add_i32 s44, s91, 0x2000
	s_cmpk_lg_i32 s91, 0x4000
	s_cselect_b32 s80, s44, 0
	s_add_i32 s41, s42, 2
	s_add_i32 s45, s42, 9
	s_waitcnt vmcnt(3) lgkmcnt(0)
	s_barrier
	s_andn2_b64 vcc, exec, s[6:7]
	s_cbranch_vccz .Lresc2_l0
; #define WAIT_BAR(N) asm volatile("s_waitcnt vmcnt(" #N ") lgkmcnt(0)\n\ts_barrier":::"memory")
;   #define RESC() do{ if(resc){ asm volatile("s_waitcnt lgkmcnt(0)":::"memory"); \
;       _Pragma("unroll") for(int d_=0;d_<2;++d_) _Pragma("unroll") for(int r=0;r<16;++r)o[d_][r]*=wsf[crow(r,hi)]; } }while(0)
;   #define ROT() do{sl_prev=sl_cur;sl_cur=sl_next;sl_next=(sl_next==(NSLOT-1)*SLOTB)?0:sl_next+SLOTB;}while(0)
;   #define RESC() do{ if(resc){ asm volatile("s_waitcnt lgkmcnt(0)":::"memory"); \
;       _Pragma("unroll") for(int d_=0;d_<4;++d_) _Pragma("unroll") for(int r=0;r<16;++r)o[d_][r]*=wsf[crow(r,hi)]; } }while(0)
;   #define ROT() do{sl_prev=sl_cur;sl_cur=sl_next;sl_next=(sl_next==(NSLOT-1)*SLOTB)?0:sl_next+SLOTB;}while(0)
; template<int THRL> __device__ __forceinline__ void attn_unit_d(int qb,const bf16*Q,const bf16*__restrict__ K,const bf16*__restrict__ V,bf16*O,const float*__restrict__ cum,const float*__restrict__ relb,const float thr,char*shm,const int wv){
;     ...
;   for(;t+NEAR<NT;t+=2){
;     STEP(pB0,pB1,pA0,pA1,t,true,true,true);     WAIT_BAR(3); RESC(); ROT();
;     STEP(pA0,pA1,pB0,pB1,t+1,true,true,true);   WAIT_BAR(3); RESC(); ROT();
;   }
.LBB0_475:
	s_cmp_ge_u32 s45, s90
	s_cbranch_scc1 .LBB0_484
	s_mov_b32 s43, s48
	s_mov_b32 s6, s40
	s_mov_b32 s48, s91
	s_mov_b32 s40, s80
	s_mov_b32 s42, s41
	s_branch .LBB0_469
.Lresc1_l0:
	s_waitcnt lgkmcnt(0)
	ds_read_b128 v[116:119], v241 offset:96
	ds_read_b128 v[120:123], v241 offset:64
	ds_read_b128 v[124:127], v241 offset:32
	ds_read_b128 v[132:135], v241
	s_waitcnt lgkmcnt(3)
	v_pk_mul_f32 v[78:79], v[78:79], v[118:119]
	s_waitcnt lgkmcnt(2)
	v_pk_mul_f32 v[74:75], v[74:75], v[122:123]
	s_waitcnt lgkmcnt(1)
	v_pk_mul_f32 v[70:71], v[70:71], v[126:127]
	s_waitcnt lgkmcnt(0)
	v_pk_mul_f32 v[66:67], v[66:67], v[134:135]
	v_pk_mul_f32 v[76:77], v[76:77], v[116:117]
	v_pk_mul_f32 v[72:73], v[72:73], v[120:121]
	v_pk_mul_f32 v[68:69], v[68:69], v[124:125]
	v_pk_mul_f32 v[64:65], v[64:65], v[132:133]
	v_pk_mul_f32 v[62:63], v[62:63], v[118:119]
	v_pk_mul_f32 v[58:59], v[58:59], v[122:123]
	v_pk_mul_f32 v[54:55], v[54:55], v[126:127]
	v_pk_mul_f32 v[50:51], v[50:51], v[134:135]
	v_pk_mul_f32 v[60:61], v[60:61], v[116:117]
	v_pk_mul_f32 v[56:57], v[56:57], v[120:121]
	v_pk_mul_f32 v[52:53], v[52:53], v[124:125]
	v_pk_mul_f32 v[48:49], v[48:49], v[132:133]
	v_pk_mul_f32 v[46:47], v[46:47], v[118:119]
	v_pk_mul_f32 v[42:43], v[42:43], v[122:123]
	v_pk_mul_f32 v[38:39], v[38:39], v[126:127]
	v_pk_mul_f32 v[34:35], v[34:35], v[134:135]
	v_pk_mul_f32 v[44:45], v[44:45], v[116:117]
	v_pk_mul_f32 v[40:41], v[40:41], v[120:121]
	v_pk_mul_f32 v[36:37], v[36:37], v[124:125]
	v_pk_mul_f32 v[32:33], v[32:33], v[132:133]
	v_pk_mul_f32 v[30:31], v[30:31], v[118:119]
	v_pk_mul_f32 v[26:27], v[26:27], v[122:123]
	v_pk_mul_f32 v[22:23], v[22:23], v[126:127]
	v_pk_mul_f32 v[18:19], v[18:19], v[134:135]
	v_pk_mul_f32 v[28:29], v[28:29], v[116:117]
	v_pk_mul_f32 v[24:25], v[24:25], v[120:121]
	v_pk_mul_f32 v[20:21], v[20:21], v[124:125]
	v_pk_mul_f32 v[16:17], v[16:17], v[132:133]
	s_branch .LBB0_472
.Lresc2_l0:
	s_waitcnt lgkmcnt(0)
	ds_read_b128 v[2:5], v241 offset:96
	ds_read_b128 v[6:9], v241 offset:64
	ds_read_b128 v[10:13], v241 offset:32
	ds_read_b128 v[112:115], v241
	s_waitcnt lgkmcnt(3)
	v_pk_mul_f32 v[78:79], v[78:79], v[4:5]
	s_waitcnt lgkmcnt(2)
	v_pk_mul_f32 v[74:75], v[74:75], v[8:9]
	s_waitcnt lgkmcnt(1)
	v_pk_mul_f32 v[70:71], v[70:71], v[12:13]
	s_waitcnt lgkmcnt(0)
	v_pk_mul_f32 v[66:67], v[66:67], v[114:115]
	v_pk_mul_f32 v[76:77], v[76:77], v[2:3]
	v_pk_mul_f32 v[72:73], v[72:73], v[6:7]
	v_pk_mul_f32 v[68:69], v[68:69], v[10:11]
	v_pk_mul_f32 v[64:65], v[64:65], v[112:113]
	v_pk_mul_f32 v[62:63], v[62:63], v[4:5]
	v_pk_mul_f32 v[58:59], v[58:59], v[8:9]
	v_pk_mul_f32 v[54:55], v[54:55], v[12:13]
	v_pk_mul_f32 v[50:51], v[50:51], v[114:115]
	v_pk_mul_f32 v[60:61], v[60:61], v[2:3]
	v_pk_mul_f32 v[56:57], v[56:57], v[6:7]
	v_pk_mul_f32 v[52:53], v[52:53], v[10:11]
	v_pk_mul_f32 v[48:49], v[48:49], v[112:113]
	v_pk_mul_f32 v[46:47], v[46:47], v[4:5]
	v_pk_mul_f32 v[42:43], v[42:43], v[8:9]
	v_pk_mul_f32 v[38:39], v[38:39], v[12:13]
	v_pk_mul_f32 v[34:35], v[34:35], v[114:115]
	v_pk_mul_f32 v[44:45], v[44:45], v[2:3]
	v_pk_mul_f32 v[40:41], v[40:41], v[6:7]
	v_pk_mul_f32 v[36:37], v[36:37], v[10:11]
	v_pk_mul_f32 v[32:33], v[32:33], v[112:113]
	v_pk_mul_f32 v[30:31], v[30:31], v[4:5]
	v_pk_mul_f32 v[26:27], v[26:27], v[8:9]
	v_pk_mul_f32 v[22:23], v[22:23], v[12:13]
	v_pk_mul_f32 v[18:19], v[18:19], v[114:115]
	v_pk_mul_f32 v[28:29], v[28:29], v[2:3]
	v_pk_mul_f32 v[24:25], v[24:25], v[6:7]
	v_pk_mul_f32 v[20:21], v[20:21], v[10:11]
	v_pk_mul_f32 v[16:17], v[16:17], v[112:113]
	s_branch .LBB0_475

; #define WAIT_BAR(N) asm volatile("s_waitcnt vmcnt(" #N ") lgkmcnt(0)\n\ts_barrier":::"memory")
;   #define RESC() do{ if(resc){ asm volatile("s_waitcnt lgkmcnt(0)":::"memory"); \
;       _Pragma("unroll") for(int d_=0;d_<2;++d_) _Pragma("unroll") for(int r=0;r<16;++r)o[d_][r]*=wsf[crow(r,hi)]; } }while(0)
;   #define ROT() do{sl_prev=sl_cur;sl_cur=sl_next;sl_next=(sl_next==(NSLOT-1)*SLOTB)?0:sl_next+SLOTB;}while(0)
;   #define RESC() do{ if(resc){ asm volatile("s_waitcnt lgkmcnt(0)":::"memory"); \
;       _Pragma("unroll") for(int d_=0;d_<4;++d_) _Pragma("unroll") for(int r=0;r<16;++r)o[d_][r]*=wsf[crow(r,hi)]; } }while(0)
;   #define ROT() do{sl_prev=sl_cur;sl_cur=sl_next;sl_next=(sl_next==(NSLOT-1)*SLOTB)?0:sl_next+SLOTB;}while(0)
; template<int THRL> __device__ __forceinline__ void attn_unit_d(int qb,const bf16*Q,const bf16*__restrict__ K,const bf16*__restrict__ V,bf16*O,const float*__restrict__ cum,const float*__restrict__ relb,const float thr,char*shm,const int wv){
;     ...
;   int t=1;
;     ...
;   constexpr int NEAR=(MODE==1)?7:5;
;   for(;t+NEAR<NT;t+=2){
;     STEP(pB0,pB1,pA0,pA1,t,true,true,true);     WAIT_BAR(3); RESC(); ROT();
.LBB0_1510:
	s_waitcnt lgkmcnt(14)
	v_mfma_f32_32x32x16_bf16 v[64:79], v[156:159], v[208:211], v[64:79]
	v_exp_f32_e32 v96, v80
	v_exp_f32_e32 v97, v81
	ds_read_b64_tr_b16 v[116:117], v212 offset:32768
	ds_read_b64_tr_b16 v[118:119], v212 offset:33280
	s_waitcnt lgkmcnt(14)
	v_mfma_f32_32x32x16_bf16 v[48:63], v[156:159], v[204:207], v[48:63]
	v_exp_f32_e32 v98, v98
	v_exp_f32_e32 v99, v99
	ds_read_b64_tr_b16 v[120:121], v212 offset:36864
	ds_read_b64_tr_b16 v[122:123], v212 offset:37376
	v_add_u32_e32 v80, s46, v248
	ds_read_b128 v[112:115], v80
	ds_read_b128 v[128:131], v80 offset:512
	s_waitcnt lgkmcnt(14)
	v_mfma_f32_32x32x16_bf16 v[64:79], v[152:155], v[10:13], v[64:79]
	v_exp_f32_e32 v100, v100
	v_exp_f32_e32 v101, v101
	ds_read_b64_tr_b16 v[124:125], v212 offset:33792
	ds_read_b64_tr_b16 v[126:127], v212 offset:34304
	ds_read_b128 v[184:187], v80 offset:2048
	ds_read_b128 v[176:179], v80 offset:2560
	v_mfma_f32_32x32x16_bf16 v[48:63], v[152:155], v[6:9], v[48:63]
	v_exp_f32_e32 v102, v102
	v_exp_f32_e32 v103, v103
	ds_read_b64_tr_b16 v[132:133], v212 offset:37888
	ds_read_b64_tr_b16 v[134:135], v212 offset:38400
	ds_read_b128 v[180:183], v80 offset:4096
	ds_read_b128 v[6:9], v80 offset:4608
	s_waitcnt lgkmcnt(14)
	v_mfma_f32_32x32x16_bf16 v[64:79], v[148:151], v[2:5], v[64:79]
	v_exp_f32_e32 v104, v104
	v_exp_f32_e32 v105, v105
	ds_read_b64_tr_b16 v[136:137], v212 offset:34816
	ds_read_b64_tr_b16 v[138:139], v212 offset:35328
	ds_read_b128 v[10:13], v80 offset:6144
	ds_read_b128 v[2:5], v80 offset:6656
	v_mfma_f32_32x32x16_bf16 v[48:63], v[148:151], v[188:191], v[48:63]
	v_exp_f32_e32 v106, v106
	v_exp_f32_e32 v107, v107
	ds_read_b64_tr_b16 v[140:141], v212 offset:38912
	ds_read_b64_tr_b16 v[142:143], v212 offset:39424
	v_mfma_f32_32x32x16_bf16 v[64:79], v[144:147], v[192:195], v[64:79]
	v_exp_f32_e32 v108, v108
	v_exp_f32_e32 v109, v109
	ds_read_b64_tr_b16 v[188:189], v212 offset:35840
	ds_read_b64_tr_b16 v[190:191], v212 offset:36352
	v_mfma_f32_32x32x16_bf16 v[48:63], v[144:147], v[196:199], v[48:63]
	v_exp_f32_e32 v110, v110
	v_exp_f32_e32 v111, v111
	ds_read_b64_tr_b16 v[192:193], v212 offset:39936
	ds_read_b64_tr_b16 v[194:195], v212 offset:40448
	s_waitcnt lgkmcnt(14)
	v_mfma_f32_32x32x16_bf16 v[32:47], v[156:159], v[116:119], v[32:47]
	v_exp_f32_e32 v80, v14
	v_exp_f32_e32 v81, v15
	v_mfma_f32_32x32x16_bf16 v[16:31], v[156:159], v[120:123], v[16:31]
	v_exp_f32_e32 v82, v82
	v_exp_f32_e32 v83, v83
	v_mfma_f32_32x32x16_bf16 v[32:47], v[152:155], v[124:127], v[32:47]
	v_exp_f32_e32 v84, v84
	v_exp_f32_e32 v85, v85
	s_waitcnt lgkmcnt(12)
	v_mfma_f32_32x32x16_bf16 v[16:31], v[152:155], v[132:135], v[16:31]
	v_exp_f32_e32 v86, v86
	v_exp_f32_e32 v87, v87
	s_waitcnt lgkmcnt(8)
	v_mfma_f32_32x32x16_bf16 v[32:47], v[148:151], v[136:139], v[32:47]
	v_exp_f32_e32 v88, v88
	v_exp_f32_e32 v89, v89
	s_waitcnt lgkmcnt(4)
	v_mfma_f32_32x32x16_bf16 v[16:31], v[148:151], v[140:143], v[16:31]
	v_exp_f32_e32 v90, v90
	v_exp_f32_e32 v91, v91
	s_waitcnt lgkmcnt(2)
	v_mfma_f32_32x32x16_bf16 v[32:47], v[144:147], v[188:191], v[32:47]
	v_exp_f32_e32 v92, v92
	v_exp_f32_e32 v93, v93
	s_waitcnt lgkmcnt(0)
	v_mfma_f32_32x32x16_bf16 v[16:31], v[144:147], v[192:195], v[16:31]
	v_exp_f32_e32 v94, v94
	v_exp_f32_e32 v95, v95
	s_add_i32 s42, s46, 0x2000
	s_cmpk_lg_i32 s46, 0x4000
	s_cselect_b32 s87, s42, 0
	s_waitcnt vmcnt(3) lgkmcnt(0)
	s_barrier
	s_andn2_b64 vcc, exec, s[10:11]
	s_cbranch_vccz .Lresc1_l1
.LBB0_1512:
	s_lshl_b32 s10, s89, 1
	v_add_u32_e32 v14, s10, v249
	ds_read_b64_tr_b16 v[192:193], v14 offset:24576
	ds_read_b64_tr_b16 v[194:195], v14 offset:25088
	v_add_f32_e32 v15, v96, v97
	v_add_f32_e32 v15, v98, v15
	v_add_f32_e32 v15, v99, v15
	v_add_f32_e32 v15, v100, v15
	v_add_f32_e32 v15, v101, v15
	v_cvt_pk_bf16_f32 v156, v96, v97
	v_cvt_pk_bf16_f32 v157, v98, v99
	v_mfma_f32_32x32x16_bf16 v[112:127], v[112:115], v[172:175], 0
	ds_read_b64_tr_b16 v[196:197], v14 offset:28672
	ds_read_b64_tr_b16 v[198:199], v14 offset:29184
	v_add_f32_e32 v15, v102, v15
	v_add_f32_e32 v15, v103, v15
	v_add_f32_e32 v15, v104, v15
	v_add_f32_e32 v15, v105, v15
	v_cvt_pk_bf16_f32 v158, v100, v101
	v_cvt_pk_bf16_f32 v159, v102, v103
	v_mfma_f32_32x32x16_bf16 v[128:143], v[128:131], v[172:175], 0
	ds_read_b64_tr_b16 v[188:189], v14 offset:25600
	ds_read_b64_tr_b16 v[190:191], v14 offset:26112
	v_add_f32_e32 v15, v106, v15
	v_add_f32_e32 v15, v107, v15
	v_add_f32_e32 v15, v108, v15
	v_add_f32_e32 v15, v109, v15
	v_cvt_pk_bf16_f32 v152, v104, v105
	v_cvt_pk_bf16_f32 v153, v106, v107
	v_mfma_f32_32x32x16_bf16 v[112:127], v[184:187], v[168:171], v[112:127]
	ds_read_b64_tr_b16 v[184:185], v14 offset:29696
	ds_read_b64_tr_b16 v[186:187], v14 offset:30208
	v_add_f32_e32 v15, v110, v15
	v_add_f32_e32 v15, v111, v15
	v_add_f32_e32 v15, v80, v15
	v_add_f32_e32 v15, v81, v15
	v_cvt_pk_bf16_f32 v154, v108, v109
	v_cvt_pk_bf16_f32 v155, v110, v111
	v_mfma_f32_32x32x16_bf16 v[128:143], v[176:179], v[168:171], v[128:143]
	ds_read_b64_tr_b16 v[176:177], v14 offset:26624
	ds_read_b64_tr_b16 v[178:179], v14 offset:27136
	v_add_f32_e32 v15, v82, v15
	v_add_f32_e32 v15, v83, v15
	v_add_f32_e32 v15, v84, v15
	v_add_f32_e32 v15, v85, v15
	v_cvt_pk_bf16_f32 v148, v80, v81
	v_cvt_pk_bf16_f32 v149, v82, v83
	v_mfma_f32_32x32x16_bf16 v[112:127], v[180:183], v[164:167], v[112:127]
	ds_read_b64_tr_b16 v[208:209], v14 offset:30720
	ds_read_b64_tr_b16 v[210:211], v14 offset:31232
	v_add_f32_e32 v15, v86, v15
	v_add_f32_e32 v15, v87, v15
	v_add_f32_e32 v15, v88, v15
	v_add_f32_e32 v15, v89, v15
	v_cvt_pk_bf16_f32 v150, v84, v85
	v_cvt_pk_bf16_f32 v151, v86, v87
	v_mfma_f32_32x32x16_bf16 v[128:143], v[6:9], v[164:167], v[128:143]
	ds_read_b64_tr_b16 v[6:7], v14 offset:27648
	ds_read_b64_tr_b16 v[8:9], v14 offset:28160
	v_add_f32_e32 v15, v90, v15
	v_add_f32_e32 v15, v91, v15
	v_add_f32_e32 v15, v92, v15
	v_add_f32_e32 v15, v93, v15
	v_cvt_pk_bf16_f32 v144, v88, v89
	v_cvt_pk_bf16_f32 v145, v90, v91
	v_mfma_f32_32x32x16_bf16 v[112:127], v[10:13], v[160:163], v[112:127]
	ds_read_b64_tr_b16 v[10:11], v14 offset:31744
	ds_read_b64_tr_b16 v[12:13], v14 offset:32256
	v_add_f32_e32 v15, v94, v15
	v_add_f32_e32 v15, v95, v15
	v_add_f32_e32 v15, 0, v15
	v_cvt_pk_bf16_f32 v146, v92, v93
	v_cvt_pk_bf16_f32 v147, v94, v95
	v_mfma_f32_32x32x16_bf16 v[128:143], v[2:5], v[160:163], v[128:143]
	s_add_i32 s10, s46, s66
	s_mov_b32 m0, s10
	s_add_i32 s48, s48, 0x8000
	buffer_load_dwordx4 v246, s[12:15], s48 offen lds
	s_lshl_b32 s10, s87, 1
	s_add_i32 s89, s49, 0x8000
	s_add_i32 s11, s10, s67
	s_mov_b32 m0, s11
	s_nop 0
	buffer_load_dwordx4 v247, s[16:19], s89 offen lds
	s_add_i32 s11, s49, 0x8080
	s_add_i32 s10, s10, s53
	s_mov_b32 m0, s10
	s_nop 0
	buffer_load_dwordx4 v247, s[16:19], s11 offen lds
	v_add_f32_e64 v4, v112, -v228
	v_add_f32_e64 v5, v113, -v228
	v_pk_add_f32 v[2:3], v[128:129], v[228:229] op_sel_hi:[1,0] neg_lo:[0,1] neg_hi:[0,1]
	v_pk_add_f32 v[98:99], v[114:115], v[228:229] op_sel_hi:[1,0] neg_lo:[0,1] neg_hi:[0,1]
	v_pk_add_f32 v[82:83], v[130:131], v[228:229] op_sel_hi:[1,0] neg_lo:[0,1] neg_hi:[0,1]
	v_max_f32_e32 v80, v4, v5
	v_pk_add_f32 v[100:101], v[116:117], v[228:229] op_sel_hi:[1,0] neg_lo:[0,1] neg_hi:[0,1]
	v_pk_add_f32 v[102:103], v[118:119], v[228:229] op_sel_hi:[1,0] neg_lo:[0,1] neg_hi:[0,1]
	v_max3_f32 v81, v98, v99, v3
	v_max3_f32 v80, v80, v2, v82
	v_pk_add_f32 v[84:85], v[132:133], v[228:229] op_sel_hi:[1,0] neg_lo:[0,1] neg_hi:[0,1]
	v_pk_add_f32 v[86:87], v[134:135], v[228:229] op_sel_hi:[1,0] neg_lo:[0,1] neg_hi:[0,1]
	v_max3_f32 v80, v80, v83, v100
	v_max3_f32 v81, v81, v102, v103
	v_pk_add_f32 v[104:105], v[120:121], v[228:229] op_sel_hi:[1,0] neg_lo:[0,1] neg_hi:[0,1]
	v_pk_add_f32 v[106:107], v[122:123], v[228:229] op_sel_hi:[1,0] neg_lo:[0,1] neg_hi:[0,1]
	v_max3_f32 v80, v80, v101, v84
	v_max3_f32 v81, v81, v86, v87
	v_pk_add_f32 v[88:89], v[136:137], v[228:229] op_sel_hi:[1,0] neg_lo:[0,1] neg_hi:[0,1]
	v_pk_add_f32 v[90:91], v[138:139], v[228:229] op_sel_hi:[1,0] neg_lo:[0,1] neg_hi:[0,1]
	v_max3_f32 v80, v80, v85, v104
	v_max3_f32 v81, v81, v106, v107
	v_pk_add_f32 v[108:109], v[124:125], v[228:229] op_sel_hi:[1,0] neg_lo:[0,1] neg_hi:[0,1]
	v_pk_add_f32 v[110:111], v[126:127], v[228:229] op_sel_hi:[1,0] neg_lo:[0,1] neg_hi:[0,1]
	v_max3_f32 v80, v80, v105, v88
	v_max3_f32 v81, v81, v90, v91
	v_pk_add_f32 v[92:93], v[140:141], v[228:229] op_sel_hi:[1,0] neg_lo:[0,1] neg_hi:[0,1]
	v_pk_add_f32 v[94:95], v[142:143], v[228:229] op_sel_hi:[1,0] neg_lo:[0,1] neg_hi:[0,1]
	v_max3_f32 v80, v80, v89, v108
	v_max3_f32 v81, v81, v110, v111
	v_max3_f32 v80, v80, v109, v92
	v_max3_f32 v81, v81, v94, v95
	v_add_f32_e32 v250, v0, v15
	v_max3_f32 v0, v80, v93, v81
	v_cmp_lt_f32_e32 vcc, s78, v0
	s_cmp_lg_u64 vcc, 0
	s_cselect_b64 s[10:11], -1, 0
	s_cbranch_vccnz .LBB0_1520
.LBB0_1513:
	s_waitcnt lgkmcnt(14)
	v_mfma_f32_32x32x16_bf16 v[64:79], v[156:159], v[192:195], v[64:79]
	v_exp_f32_e32 v96, v4
	v_exp_f32_e32 v97, v5
	ds_read_b64_tr_b16 v[112:113], v14 offset:32768
	ds_read_b64_tr_b16 v[114:115], v14 offset:33280
	s_waitcnt lgkmcnt(14)
	v_mfma_f32_32x32x16_bf16 v[48:63], v[156:159], v[196:199], v[48:63]
	v_exp_f32_e32 v98, v98
	v_exp_f32_e32 v99, v99
	ds_read_b64_tr_b16 v[116:117], v14 offset:36864
	ds_read_b64_tr_b16 v[118:119], v14 offset:37376
	v_add_u32_e32 v0, s87, v248
	ds_read_b128 v[204:207], v0
	ds_read_b128 v[200:203], v0 offset:512
	s_waitcnt lgkmcnt(14)
	v_mfma_f32_32x32x16_bf16 v[64:79], v[152:155], v[188:191], v[64:79]
	v_exp_f32_e32 v100, v100
	v_exp_f32_e32 v101, v101
	ds_read_b64_tr_b16 v[120:121], v14 offset:33792
	ds_read_b64_tr_b16 v[122:123], v14 offset:34304
	ds_read_b128 v[196:199], v0 offset:2048
	ds_read_b128 v[192:195], v0 offset:2560
	v_mfma_f32_32x32x16_bf16 v[48:63], v[152:155], v[184:187], v[48:63]
	v_exp_f32_e32 v102, v102
	v_exp_f32_e32 v103, v103
	ds_read_b64_tr_b16 v[124:125], v14 offset:37888
	ds_read_b64_tr_b16 v[126:127], v14 offset:38400
	ds_read_b128 v[188:191], v0 offset:4096
	ds_read_b128 v[184:187], v0 offset:4608
	s_waitcnt lgkmcnt(14)
	v_mfma_f32_32x32x16_bf16 v[64:79], v[148:151], v[176:179], v[64:79]
	v_exp_f32_e32 v104, v104
	v_exp_f32_e32 v105, v105
	ds_read_b64_tr_b16 v[128:129], v14 offset:34816
	ds_read_b64_tr_b16 v[130:131], v14 offset:35328
	ds_read_b128 v[180:183], v0 offset:6144
	ds_read_b128 v[176:179], v0 offset:6656
	v_mfma_f32_32x32x16_bf16 v[48:63], v[148:151], v[208:211], v[48:63]
	v_exp_f32_e32 v106, v106
	v_exp_f32_e32 v107, v107
	ds_read_b64_tr_b16 v[132:133], v14 offset:38912
	ds_read_b64_tr_b16 v[134:135], v14 offset:39424
	v_mfma_f32_32x32x16_bf16 v[64:79], v[144:147], v[6:9], v[64:79]
	v_exp_f32_e32 v108, v108
	v_exp_f32_e32 v109, v109
	ds_read_b64_tr_b16 v[4:5], v14 offset:35840
	ds_read_b64_tr_b16 v[6:7], v14 offset:36352
	v_mfma_f32_32x32x16_bf16 v[48:63], v[144:147], v[10:13], v[48:63]
	v_exp_f32_e32 v110, v110
	v_exp_f32_e32 v111, v111
	ds_read_b64_tr_b16 v[8:9], v14 offset:39936
	ds_read_b64_tr_b16 v[10:11], v14 offset:40448
	s_waitcnt lgkmcnt(14)
	v_mfma_f32_32x32x16_bf16 v[32:47], v[156:159], v[112:115], v[32:47]
	v_exp_f32_e32 v80, v2
	v_exp_f32_e32 v81, v3
	v_mfma_f32_32x32x16_bf16 v[16:31], v[156:159], v[116:119], v[16:31]
	v_exp_f32_e32 v82, v82
	v_exp_f32_e32 v83, v83
	v_mfma_f32_32x32x16_bf16 v[32:47], v[152:155], v[120:123], v[32:47]
	v_exp_f32_e32 v84, v84
	v_exp_f32_e32 v85, v85
	s_waitcnt lgkmcnt(12)
	v_mfma_f32_32x32x16_bf16 v[16:31], v[152:155], v[124:127], v[16:31]
	v_exp_f32_e32 v86, v86
	v_exp_f32_e32 v87, v87
	s_waitcnt lgkmcnt(8)
	v_mfma_f32_32x32x16_bf16 v[32:47], v[148:151], v[128:131], v[32:47]
	v_exp_f32_e32 v88, v88
	v_exp_f32_e32 v89, v89
	s_waitcnt lgkmcnt(4)
	v_mfma_f32_32x32x16_bf16 v[16:31], v[148:151], v[132:135], v[16:31]
	v_exp_f32_e32 v90, v90
	v_exp_f32_e32 v91, v91
	s_waitcnt lgkmcnt(2)
	v_mfma_f32_32x32x16_bf16 v[32:47], v[144:147], v[4:7], v[32:47]
	v_exp_f32_e32 v92, v92
	v_exp_f32_e32 v93, v93
	s_waitcnt lgkmcnt(0)
	v_mfma_f32_32x32x16_bf16 v[16:31], v[144:147], v[8:11], v[16:31]
	v_exp_f32_e32 v94, v94
	v_exp_f32_e32 v95, v95
	s_add_i32 s42, s87, 0x2000
	s_cmpk_lg_i32 s87, 0x4000
	s_cselect_b32 s88, s42, 0
	s_add_i32 s48, s47, 2
	s_add_i32 s43, s47, 9
	s_waitcnt vmcnt(3) lgkmcnt(0)
	s_barrier
	s_andn2_b64 vcc, exec, s[10:11]
	s_cbranch_vccz .Lresc2_l1
; #define WAIT_BAR(N) asm volatile("s_waitcnt vmcnt(" #N ") lgkmcnt(0)\n\ts_barrier":::"memory")
;   #define RESC() do{ if(resc){ asm volatile("s_waitcnt lgkmcnt(0)":::"memory"); \
;       _Pragma("unroll") for(int d_=0;d_<2;++d_) _Pragma("unroll") for(int r=0;r<16;++r)o[d_][r]*=wsf[crow(r,hi)]; } }while(0)
;   #define ROT() do{sl_prev=sl_cur;sl_cur=sl_next;sl_next=(sl_next==(NSLOT-1)*SLOTB)?0:sl_next+SLOTB;}while(0)
;   #define RESC() do{ if(resc){ asm volatile("s_waitcnt lgkmcnt(0)":::"memory"); \
;       _Pragma("unroll") for(int d_=0;d_<4;++d_) _Pragma("unroll") for(int r=0;r<16;++r)o[d_][r]*=wsf[crow(r,hi)]; } }while(0)
;   #define ROT() do{sl_prev=sl_cur;sl_cur=sl_next;sl_next=(sl_next==(NSLOT-1)*SLOTB)?0:sl_next+SLOTB;}while(0)
; template<int THRL> __device__ __forceinline__ void attn_unit_d(int qb,const bf16*Q,const bf16*__restrict__ K,const bf16*__restrict__ V,bf16*O,const float*__restrict__ cum,const float*__restrict__ relb,const float thr,char*shm,const int wv){
;     ...
;   for(;t+NEAR<NT;t+=2){
;     STEP(pB0,pB1,pA0,pA1,t,true,true,true);     WAIT_BAR(3); RESC(); ROT();
;     STEP(pA0,pA1,pB0,pB1,t+1,true,true,true);   WAIT_BAR(3); RESC(); ROT();
;   }
.LBB0_1515:
	s_cmp_ge_u32 s43, s86
	s_cbranch_scc1 .LBB0_1524
	s_mov_b32 s49, s89
	s_mov_b32 s10, s46
	s_mov_b32 s89, s87
	s_mov_b32 s46, s88
	s_mov_b32 s47, s48
	s_branch .LBB0_1509
.Lresc1_l1:
	s_waitcnt lgkmcnt(0)
	ds_read_b128 v[116:119], v240 offset:96
	ds_read_b128 v[120:123], v240 offset:64
	ds_read_b128 v[124:127], v240 offset:32
	ds_read_b128 v[132:135], v240
	s_waitcnt lgkmcnt(3)
	v_pk_mul_f32 v[78:79], v[78:79], v[118:119]
	s_waitcnt lgkmcnt(2)
	v_pk_mul_f32 v[74:75], v[74:75], v[122:123]
	s_waitcnt lgkmcnt(1)
	v_pk_mul_f32 v[70:71], v[70:71], v[126:127]
	s_waitcnt lgkmcnt(0)
	v_pk_mul_f32 v[66:67], v[66:67], v[134:135]
	v_pk_mul_f32 v[76:77], v[76:77], v[116:117]
	v_pk_mul_f32 v[72:73], v[72:73], v[120:121]
	v_pk_mul_f32 v[68:69], v[68:69], v[124:125]
	v_pk_mul_f32 v[64:65], v[64:65], v[132:133]
	v_pk_mul_f32 v[62:63], v[62:63], v[118:119]
	v_pk_mul_f32 v[58:59], v[58:59], v[122:123]
	v_pk_mul_f32 v[54:55], v[54:55], v[126:127]
	v_pk_mul_f32 v[50:51], v[50:51], v[134:135]
	v_pk_mul_f32 v[60:61], v[60:61], v[116:117]
	v_pk_mul_f32 v[56:57], v[56:57], v[120:121]
	v_pk_mul_f32 v[52:53], v[52:53], v[124:125]
	v_pk_mul_f32 v[48:49], v[48:49], v[132:133]
	v_pk_mul_f32 v[46:47], v[46:47], v[118:119]
	v_pk_mul_f32 v[42:43], v[42:43], v[122:123]
	v_pk_mul_f32 v[38:39], v[38:39], v[126:127]
	v_pk_mul_f32 v[34:35], v[34:35], v[134:135]
	v_pk_mul_f32 v[44:45], v[44:45], v[116:117]
	v_pk_mul_f32 v[40:41], v[40:41], v[120:121]
	v_pk_mul_f32 v[36:37], v[36:37], v[124:125]
	v_pk_mul_f32 v[32:33], v[32:33], v[132:133]
	v_pk_mul_f32 v[30:31], v[30:31], v[118:119]
	v_pk_mul_f32 v[26:27], v[26:27], v[122:123]
	v_pk_mul_f32 v[22:23], v[22:23], v[126:127]
	v_pk_mul_f32 v[18:19], v[18:19], v[134:135]
	v_pk_mul_f32 v[28:29], v[28:29], v[116:117]
	v_pk_mul_f32 v[24:25], v[24:25], v[120:121]
	v_pk_mul_f32 v[20:21], v[20:21], v[124:125]
	v_pk_mul_f32 v[16:17], v[16:17], v[132:133]
	s_branch .LBB0_1512
.Lresc2_l1:
	s_waitcnt lgkmcnt(0)
	ds_read_b128 v[2:5], v240 offset:96
	ds_read_b128 v[6:9], v240 offset:64
	ds_read_b128 v[10:13], v240 offset:32
	ds_read_b128 v[112:115], v240
	s_waitcnt lgkmcnt(3)
	v_pk_mul_f32 v[78:79], v[78:79], v[4:5]
	s_waitcnt lgkmcnt(2)
	v_pk_mul_f32 v[74:75], v[74:75], v[8:9]
	s_waitcnt lgkmcnt(1)
	v_pk_mul_f32 v[70:71], v[70:71], v[12:13]
	s_waitcnt lgkmcnt(0)
	v_pk_mul_f32 v[66:67], v[66:67], v[114:115]
	v_pk_mul_f32 v[76:77], v[76:77], v[2:3]
	v_pk_mul_f32 v[72:73], v[72:73], v[6:7]
	v_pk_mul_f32 v[68:69], v[68:69], v[10:11]
	v_pk_mul_f32 v[64:65], v[64:65], v[112:113]
	v_pk_mul_f32 v[62:63], v[62:63], v[4:5]
	v_pk_mul_f32 v[58:59], v[58:59], v[8:9]
	v_pk_mul_f32 v[54:55], v[54:55], v[12:13]
	v_pk_mul_f32 v[50:51], v[50:51], v[114:115]
	v_pk_mul_f32 v[60:61], v[60:61], v[2:3]
	v_pk_mul_f32 v[56:57], v[56:57], v[6:7]
	v_pk_mul_f32 v[52:53], v[52:53], v[10:11]
	v_pk_mul_f32 v[48:49], v[48:49], v[112:113]
	v_pk_mul_f32 v[46:47], v[46:47], v[4:5]
	v_pk_mul_f32 v[42:43], v[42:43], v[8:9]
	v_pk_mul_f32 v[38:39], v[38:39], v[12:13]
	v_pk_mul_f32 v[34:35], v[34:35], v[114:115]
	v_pk_mul_f32 v[44:45], v[44:45], v[2:3]
	v_pk_mul_f32 v[40:41], v[40:41], v[6:7]
	v_pk_mul_f32 v[36:37], v[36:37], v[10:11]
	v_pk_mul_f32 v[32:33], v[32:33], v[112:113]
	v_pk_mul_f32 v[30:31], v[30:31], v[4:5]
	v_pk_mul_f32 v[26:27], v[26:27], v[8:9]
	v_pk_mul_f32 v[22:23], v[22:23], v[12:13]
	v_pk_mul_f32 v[18:19], v[18:19], v[114:115]
	v_pk_mul_f32 v[28:29], v[28:29], v[2:3]
	v_pk_mul_f32 v[24:25], v[24:25], v[6:7]
	v_pk_mul_f32 v[20:21], v[20:21], v[10:11]
	v_pk_mul_f32 v[16:17], v[16:17], v[112:113]
	s_branch .LBB0_1515
